# ret_merge: twelve row loads in flight; dn_chunkprep: item-start loads issued together (on top of v8)
# baseline (speedup 1.0000x reference)
; DI float sum16(float v) { v = sum8(v); v += dpp_f<0x140>(v); return v; }
; DI void phase_ret_merge(PrmC p, int nrows, int gw, int NGW) {
;     ...
;     for (int row = gw; row < nrows; row += NGW) {
;         uint4 ra[4], rc[4], rz[4];
; #pragma unroll
;         for (int g = 0; g < 4; ++g) { const size_t off = (size_t)row * 2048 + g * 512 + lane * 8;
;             ra[g] = *(const uint4*)(ORp + off); rc[g] = *(const uint4*)(ORp + (size_t)T_ALL * 2048 + off); rz[g] = *(const uint4*)(PG + off); }
; #pragma unroll
;         for (int g = 0; g < 4; ++g) {
;             const size_t off = (size_t)row * 2048 + g * 512 + lane * 8;
;             float a[8], c[8], z[8]; unpack8(ra[g], a); unpack8(rc[g], c); unpack8(rz[g], z);
;             float ss = 0.f;
; #pragma unroll
;             for (int e = 0; e < 8; ++e) { a[e] += c[e]; ss += a[e] * a[e]; }
;             ss = sum16(ss); ss += __shfl_xor(ss, 16);
;             const float rstd = rsqrtf(ss * (1.0f / 256.0f) + 1e-6f);
.LBB0_284:
	s_add_i32 s6, s5, 0xffffc000
	s_mov_b32 s7, s36
	s_add_u32 s12, s8, 0x4a4a000
	s_addc_u32 s13, s9, 0
	s_lshl_b64 s[6:7], s[6:7], 11
	s_add_u32 s6, s18, s6
	s_addc_u32 s7, s19, s7
	s_add_u32 s14, s8, 0x4a4a800
	s_addc_u32 s15, s9, 0
	s_add_u32 s21, s6, 0x400000
	s_addc_u32 s25, s7, 0
	s_add_u32 s4, s8, 0x4a4ac00
	s_addc_u32 s16, s9, 0
	s_add_u32 s20, s6, 0x400400
	s_addc_u32 s17, s7, 0
	s_cmpk_lt_i32 s5, 0x4000
	v_lshl_add_u64 v[2:3], s[8:9], 0, v[0:1]
	s_cselect_b32 s12, s12, s6
	s_mov_b32 s6, 0xce4a000
	v_add_co_u32_e32 v10, vcc, s6, v2
	s_mov_b32 s6, 0x1164a000
	s_nop 0
	v_addc_co_u32_e32 v11, vcc, 0, v3, vcc
	v_add_co_u32_e32 v12, vcc, s6, v2
	s_mov_b32 s6, 0x15e4a000
	s_nop 0
	v_addc_co_u32_e32 v13, vcc, 0, v3, vcc
	global_load_dwordx4 v[16:19], v[10:11], off
	global_load_dwordx4 v[20:23], v[12:13], off
	v_add_co_u32_e32 v14, vcc, s6, v2
	s_cselect_b32 s13, s13, s7
	s_nop 0
	v_addc_co_u32_e32 v15, vcc, 0, v3, vcc
	global_load_dwordx4 v[24:27], v[14:15], off
	global_load_dwordx4 v[64:67], v[10:11], off offset:1024
	global_load_dwordx4 v[68:71], v[12:13], off offset:1024
	global_load_dwordx4 v[72:75], v[14:15], off offset:1024
	global_load_dwordx4 v[76:79], v[10:11], off offset:2048
	global_load_dwordx4 v[80:83], v[12:13], off offset:2048
	global_load_dwordx4 v[84:87], v[14:15], off offset:2048
	global_load_dwordx4 v[88:91], v[10:11], off offset:3072
	global_load_dwordx4 v[92:95], v[12:13], off offset:3072
	global_load_dwordx4 v[96:99], v[14:15], off offset:3072
	s_cselect_b32 s15, s15, s25
	s_cselect_b32 s14, s14, s21
	s_cselect_b32 s17, s16, s17
	s_cselect_b32 s16, s4, s20
	s_add_i32 s5, s5, s64
	s_add_u32 s8, s8, s10
	s_addc_u32 s9, s9, s11
	s_cmp_ge_i32 s5, s27
	s_waitcnt vmcnt(9)
	v_lshlrev_b32_e32 v3, 16, v17
	v_lshlrev_b32_e32 v2, 16, v16
	v_and_b32_e32 v7, 0xffff0000, v17
	v_and_b32_e32 v6, 0xffff0000, v16
	v_lshlrev_b32_e32 v5, 16, v21
	v_lshlrev_b32_e32 v4, 16, v20
	v_and_b32_e32 v9, 0xffff0000, v21
	v_and_b32_e32 v8, 0xffff0000, v20
	v_pk_add_f32 v[4:5], v[2:3], v[4:5]
	v_pk_add_f32 v[2:3], v[6:7], v[8:9]
	v_and_b32_e32 v21, 0xffff0000, v24
	v_mov_b32_e32 v6, v3
	v_mov_b32_e32 v7, v5
	v_lshlrev_b32_e32 v16, 16, v25
	v_lshlrev_b32_e32 v17, 16, v24
	v_pk_mul_f32 v[28:29], v[6:7], v[6:7]
	v_mul_f32_e32 v7, 0xbfb8aa3b, v21
	v_mul_f32_e32 v6, 0xbfb8aa3b, v17
	v_exp_f32_e32 v8, v7
	v_mul_f32_e32 v7, 0xbfb8aa3b, v16
	v_exp_f32_e32 v6, v6
	v_exp_f32_e32 v7, v7
	v_and_b32_e32 v20, 0xffff0000, v25
	v_pk_add_f32 v[6:7], v[6:7], 1.0 op_sel_hi:[1,0]
	s_nop 0
	v_div_scale_f32 v9, s[6:7], v7, v7, v16
	v_rcp_f32_e32 v24, v9
	s_nop 0
	v_fma_f32 v25, -v9, v24, 1.0
	v_fmac_f32_e32 v24, v25, v24
	v_div_scale_f32 v25, vcc, v16, v7, v16
	v_mul_f32_e32 v30, v25, v24
	v_fma_f32 v31, -v9, v30, v25
	v_fmac_f32_e32 v30, v31, v24
	v_fma_f32 v9, -v9, v30, v25
	v_div_fmas_f32 v9, v9, v24, v30
	v_div_fixup_f32 v7, v9, v7, v16
	v_div_scale_f32 v9, s[6:7], v6, v6, v17
	v_rcp_f32_e32 v16, v9
	s_nop 0
	v_fma_f32 v24, -v9, v16, 1.0
	v_fmac_f32_e32 v16, v24, v16
	v_div_scale_f32 v24, vcc, v17, v6, v17
	v_mul_f32_e32 v25, v24, v16
	v_fma_f32 v30, -v9, v25, v24
	v_fmac_f32_e32 v25, v30, v16
	v_fma_f32 v9, -v9, v25, v24
	v_div_fmas_f32 v9, v9, v16, v25
	v_div_fixup_f32 v6, v9, v6, v17
	v_mul_f32_e32 v9, 0xbfb8aa3b, v20
	v_exp_f32_e32 v9, v9
	s_nop 0
	v_pk_add_f32 v[8:9], v[8:9], 1.0 op_sel_hi:[1,0]
	s_nop 0
	v_div_scale_f32 v16, s[6:7], v9, v9, v20
	v_rcp_f32_e32 v17, v16
	s_nop 0
	v_fma_f32 v24, -v16, v17, 1.0
	v_fmac_f32_e32 v17, v24, v17
	v_div_scale_f32 v24, vcc, v20, v9, v20
	v_mul_f32_e32 v25, v24, v17
	v_fma_f32 v30, -v16, v25, v24
	v_fmac_f32_e32 v25, v30, v17
	v_fma_f32 v16, -v16, v25, v24
	v_div_fmas_f32 v16, v16, v17, v25
	v_div_fixup_f32 v9, v16, v9, v20
	v_div_scale_f32 v16, s[6:7], v8, v8, v21
	v_rcp_f32_e32 v17, v16
	s_nop 0
	v_fma_f32 v20, -v16, v17, 1.0
	v_fmac_f32_e32 v17, v20, v17
	v_div_scale_f32 v20, vcc, v21, v8, v21
	v_mul_f32_e32 v24, v20, v17
	v_fma_f32 v25, -v16, v24, v20
	v_fmac_f32_e32 v24, v25, v17
	v_fma_f32 v16, -v16, v24, v20
	v_div_fmas_f32 v16, v16, v17, v24
	v_div_fixup_f32 v8, v16, v8, v21
	v_lshlrev_b32_e32 v17, 16, v19
	v_lshlrev_b32_e32 v16, 16, v18
	v_and_b32_e32 v21, 0xffff0000, v19
	v_and_b32_e32 v20, 0xffff0000, v18
	v_lshlrev_b32_e32 v19, 16, v23
	v_lshlrev_b32_e32 v18, 16, v22
	v_and_b32_e32 v23, 0xffff0000, v23
	v_and_b32_e32 v22, 0xffff0000, v22
	v_pk_add_f32 v[18:19], v[16:17], v[18:19]
	v_pk_add_f32 v[16:17], v[20:21], v[22:23]
	v_mov_b32_e32 v21, v18
	v_mov_b32_e32 v20, v16
	v_lshlrev_b32_e32 v25, 16, v26
	v_and_b32_e32 v26, 0xffff0000, v26
	v_pk_mul_f32 v[42:43], v[20:21], v[20:21]
	v_mov_b32_e32 v20, v17
	v_mov_b32_e32 v21, v19
	v_lshlrev_b32_e32 v24, 16, v27
	v_pk_mul_f32 v[46:47], v[20:21], v[20:21]
	v_mul_f32_e32 v21, 0xbfb8aa3b, v26
	v_mul_f32_e32 v20, 0xbfb8aa3b, v25
	v_exp_f32_e32 v22, v21
	v_mul_f32_e32 v21, 0xbfb8aa3b, v24
	v_exp_f32_e32 v20, v20
	v_exp_f32_e32 v21, v21
	v_and_b32_e32 v27, 0xffff0000, v27
	v_pk_add_f32 v[20:21], v[20:21], 1.0 op_sel_hi:[1,0]
	s_nop 0
	v_div_scale_f32 v23, s[6:7], v21, v21, v24
	v_rcp_f32_e32 v30, v23
	s_nop 0
	v_fma_f32 v31, -v23, v30, 1.0
	v_fmac_f32_e32 v30, v31, v30
	v_div_scale_f32 v31, vcc, v24, v21, v24
	v_mul_f32_e32 v32, v31, v30
	v_fma_f32 v33, -v23, v32, v31
	v_fmac_f32_e32 v32, v33, v30
	v_fma_f32 v23, -v23, v32, v31
	v_div_fmas_f32 v23, v23, v30, v32
	v_div_fixup_f32 v21, v23, v21, v24
	v_div_scale_f32 v23, s[6:7], v20, v20, v25
	v_rcp_f32_e32 v24, v23
	s_nop 0
	v_fma_f32 v30, -v23, v24, 1.0
	v_fmac_f32_e32 v24, v30, v24
	v_div_scale_f32 v30, vcc, v25, v20, v25
	v_mul_f32_e32 v31, v30, v24
	v_fma_f32 v32, -v23, v31, v30
	v_fmac_f32_e32 v31, v32, v24
	v_fma_f32 v23, -v23, v31, v30
	v_div_fmas_f32 v23, v23, v24, v31
	v_div_fixup_f32 v20, v23, v20, v25
	v_mul_f32_e32 v23, 0xbfb8aa3b, v27
	v_exp_f32_e32 v23, v23
	s_nop 0
	v_pk_add_f32 v[22:23], v[22:23], 1.0 op_sel_hi:[1,0]
	s_nop 0
	v_div_scale_f32 v24, s[6:7], v23, v23, v27
	v_rcp_f32_e32 v25, v24
	s_nop 0
	v_fma_f32 v30, -v24, v25, 1.0
	v_fmac_f32_e32 v25, v30, v25
	v_div_scale_f32 v30, vcc, v27, v23, v27
	v_mul_f32_e32 v31, v30, v25
	v_fma_f32 v32, -v24, v31, v30
	v_fmac_f32_e32 v31, v32, v25
	v_fma_f32 v24, -v24, v31, v30
	v_div_fmas_f32 v24, v24, v25, v31
	v_div_fixup_f32 v27, v24, v23, v27
	v_div_scale_f32 v23, s[6:7], v22, v22, v26
	v_rcp_f32_e32 v24, v23
	s_nop 0
	v_fma_f32 v25, -v23, v24, 1.0
	v_fmac_f32_e32 v24, v25, v24
	v_div_scale_f32 v25, vcc, v26, v22, v26
	v_mul_f32_e32 v30, v25, v24
	v_fma_f32 v31, -v23, v30, v25
	v_fmac_f32_e32 v30, v31, v24
	v_fma_f32 v23, -v23, v30, v25
	v_div_fmas_f32 v23, v23, v24, v30
	s_waitcnt vmcnt(6)
; template <int CTRL> DI float dpp_f(float v) { return __int_as_float(__builtin_amdgcn_update_dpp(0, __float_as_int(v), CTRL, 0xF, 0xF, true)); }
; DI float sum4(float v)  { v += dpp_f<0xB1>(v); v += dpp_f<0x4E>(v); return v; }
; DI float sum8(float v)  { v = sum4(v); v += dpp_f<0x141>(v); return v; }
; DI float sum16(float v) { v = sum8(v); v += dpp_f<0x140>(v); return v; }
; DI float wave_sum(float v) {
; #pragma unroll
;     for (int o = 1; o < 64; o <<= 1) v += __shfl_xor(v, o);
;     return v;
; }
; DI float silu_f(float g) { return g / (1.0f + __expf(-g)); }
; DI void phase_ret_merge(PrmC p, int nrows, int gw, int NGW) {
;     ...
;         for (int g = 0; g < 4; ++g) {
;             const size_t off = (size_t)row * 2048 + g * 512 + lane * 8;
;             float a[8], c[8], z[8]; unpack8(ra[g], a); unpack8(rc[g], c); unpack8(rz[g], z);
;             float ss = 0.f;
; #pragma unroll
;             for (int e = 0; e < 8; ++e) { a[e] += c[e]; ss += a[e] * a[e]; }
;             ss = sum16(ss); ss += __shfl_xor(ss, 16);
;             const float rstd = rsqrtf(ss * (1.0f / 256.0f) + 1e-6f);
; #pragma unroll
;             for (int e = 0; e < 8; ++e) a[e] = a[e] * rstd * silu_f(z[e]);
	v_mov_b64_e32 v[30:31], v[64:65]
	v_mov_b64_e32 v[32:33], v[66:67]
	v_mov_b64_e32 v[34:35], v[68:69]
	v_mov_b64_e32 v[36:37], v[70:71]
	v_mov_b64_e32 v[38:39], v[72:73]
	v_mov_b64_e32 v[40:41], v[74:75]
	v_div_fixup_f32 v26, v23, v22, v26
	v_lshlrev_b32_e32 v23, 16, v31
	v_lshlrev_b32_e32 v22, 16, v30
	v_and_b32_e32 v31, 0xffff0000, v31
	v_and_b32_e32 v30, 0xffff0000, v30
	v_lshlrev_b32_e32 v25, 16, v35
	v_lshlrev_b32_e32 v24, 16, v34
	v_and_b32_e32 v35, 0xffff0000, v35
	v_and_b32_e32 v34, 0xffff0000, v34
	v_pk_add_f32 v[24:25], v[22:23], v[24:25]
	v_pk_add_f32 v[22:23], v[30:31], v[34:35]
	v_lshlrev_b32_e32 v50, 16, v39
	v_lshlrev_b32_e32 v51, 16, v38
	v_and_b32_e32 v52, 0xffff0000, v39
	v_and_b32_e32 v53, 0xffff0000, v38
	v_mov_b32_e32 v30, v23
	v_mov_b32_e32 v31, v25
	v_mov_b32_e32 v38, v22
	v_mov_b32_e32 v39, v2
	v_pk_mul_f32 v[30:31], v[30:31], v[30:31]
	v_mov_b32_e32 v34, v24
	v_mov_b32_e32 v35, v4
	v_pk_mul_f32 v[38:39], v[38:39], v[38:39]
	v_and_b32_e32 v54, 0xffff0000, v41
	v_pk_fma_f32 v[34:35], v[34:35], v[34:35], v[38:39]
	v_mov_b32_e32 v38, v31
	v_mov_b32_e32 v39, v29
	v_pk_add_f32 v[34:35], v[34:35], v[38:39]
	v_mov_b32_e32 v31, v28
	v_mul_f32_e32 v29, 0xbfb8aa3b, v53
	v_pk_add_f32 v[48:49], v[30:31], v[34:35]
	v_mul_f32_e32 v28, 0xbfb8aa3b, v51
	v_exp_f32_e32 v30, v29
	v_mul_f32_e32 v29, 0xbfb8aa3b, v50
	v_exp_f32_e32 v28, v28
	v_exp_f32_e32 v29, v29
	v_and_b32_e32 v55, 0xffff0000, v40
	v_pk_add_f32 v[28:29], v[28:29], 1.0 op_sel_hi:[1,0]
	s_nop 0
	v_div_scale_f32 v31, s[6:7], v29, v29, v50
	v_rcp_f32_e32 v34, v31
	s_nop 0
	v_fma_f32 v35, -v31, v34, 1.0
	v_fmac_f32_e32 v34, v35, v34
	v_div_scale_f32 v35, vcc, v50, v29, v50
	v_mul_f32_e32 v38, v35, v34
	v_fma_f32 v39, -v31, v38, v35
	v_fmac_f32_e32 v38, v39, v34
	v_fma_f32 v31, -v31, v38, v35
	v_div_fmas_f32 v31, v31, v34, v38
	v_div_fixup_f32 v29, v31, v29, v50
	v_div_scale_f32 v31, s[6:7], v28, v28, v51
	v_rcp_f32_e32 v34, v31
	s_nop 0
	v_fma_f32 v35, -v31, v34, 1.0
	v_fmac_f32_e32 v34, v35, v34
	v_div_scale_f32 v35, vcc, v51, v28, v51
	v_mul_f32_e32 v38, v35, v34
	v_fma_f32 v39, -v31, v38, v35
	v_fmac_f32_e32 v38, v39, v34
	v_fma_f32 v31, -v31, v38, v35
	v_div_fmas_f32 v31, v31, v34, v38
	v_div_fixup_f32 v28, v31, v28, v51
	v_mul_f32_e32 v31, 0xbfb8aa3b, v52
	v_exp_f32_e32 v31, v31
	s_nop 0
	v_pk_add_f32 v[30:31], v[30:31], 1.0 op_sel_hi:[1,0]
	s_nop 0
	v_div_scale_f32 v34, s[6:7], v31, v31, v52
	v_rcp_f32_e32 v35, v34
	s_nop 0
	v_fma_f32 v38, -v34, v35, 1.0
	v_fmac_f32_e32 v35, v38, v35
	v_div_scale_f32 v38, vcc, v52, v31, v52
	v_mul_f32_e32 v39, v38, v35
	v_fma_f32 v50, -v34, v39, v38
	v_fmac_f32_e32 v39, v50, v35
	v_fma_f32 v34, -v34, v39, v38
	v_div_fmas_f32 v34, v34, v35, v39
	v_div_fixup_f32 v31, v34, v31, v52
	v_div_scale_f32 v34, s[6:7], v30, v30, v53
	v_rcp_f32_e32 v35, v34
	v_lshlrev_b32_e32 v52, 16, v41
	v_fma_f32 v38, -v34, v35, 1.0
	v_fmac_f32_e32 v35, v38, v35
	v_div_scale_f32 v38, vcc, v53, v30, v53
	v_mul_f32_e32 v39, v38, v35
	v_fma_f32 v50, -v34, v39, v38
	v_fmac_f32_e32 v39, v50, v35
	v_fma_f32 v34, -v34, v39, v38
	v_div_fmas_f32 v34, v34, v35, v39
	v_div_fixup_f32 v30, v34, v30, v53
	v_lshlrev_b32_e32 v35, 16, v33
	v_lshlrev_b32_e32 v34, 16, v32
	v_and_b32_e32 v33, 0xffff0000, v33
	v_and_b32_e32 v32, 0xffff0000, v32
	v_lshlrev_b32_e32 v39, 16, v37
	v_lshlrev_b32_e32 v38, 16, v36
	v_and_b32_e32 v37, 0xffff0000, v37
	v_and_b32_e32 v36, 0xffff0000, v36
	v_pk_add_f32 v[34:35], v[34:35], v[38:39]
	v_pk_add_f32 v[32:33], v[32:33], v[36:37]
	v_mov_b32_e32 v37, v34
	v_mov_b32_e32 v36, v32
	v_lshlrev_b32_e32 v53, 16, v40
	v_pk_mul_f32 v[40:41], v[36:37], v[36:37]
	v_mov_b32_e32 v36, v33
	v_mov_b32_e32 v37, v35
	v_pk_mul_f32 v[50:51], v[36:37], v[36:37]
	v_mul_f32_e32 v37, 0xbfb8aa3b, v55
	v_mul_f32_e32 v36, 0xbfb8aa3b, v53
	v_exp_f32_e32 v38, v37
	v_mul_f32_e32 v37, 0xbfb8aa3b, v52
	v_exp_f32_e32 v36, v36
	v_exp_f32_e32 v37, v37
	s_nop 0
	v_pk_add_f32 v[36:37], v[36:37], 1.0 op_sel_hi:[1,0]
	s_nop 0
	v_div_scale_f32 v39, s[6:7], v37, v37, v52
	v_rcp_f32_e32 v56, v39
	s_nop 0
	v_fma_f32 v57, -v39, v56, 1.0
	v_fmac_f32_e32 v56, v57, v56
	v_div_scale_f32 v57, vcc, v52, v37, v52
	v_mul_f32_e32 v58, v57, v56
	v_fma_f32 v59, -v39, v58, v57
	v_fmac_f32_e32 v58, v59, v56
	v_fma_f32 v39, -v39, v58, v57
	v_div_fmas_f32 v39, v39, v56, v58
	v_div_fixup_f32 v37, v39, v37, v52
	v_div_scale_f32 v39, s[6:7], v36, v36, v53
	v_rcp_f32_e32 v52, v39
	s_nop 0
	v_fma_f32 v56, -v39, v52, 1.0
	v_fmac_f32_e32 v52, v56, v52
	v_div_scale_f32 v56, vcc, v53, v36, v53
	v_mul_f32_e32 v57, v56, v52
	v_fma_f32 v58, -v39, v57, v56
	v_fmac_f32_e32 v57, v58, v52
	v_fma_f32 v39, -v39, v57, v56
	v_div_fmas_f32 v39, v39, v52, v57
	v_div_fixup_f32 v36, v39, v36, v53
	v_mul_f32_e32 v39, 0xbfb8aa3b, v54
	v_exp_f32_e32 v39, v39
	s_nop 0
	v_pk_add_f32 v[38:39], v[38:39], 1.0 op_sel_hi:[1,0]
	s_nop 0
	v_div_scale_f32 v52, s[6:7], v39, v39, v54
	v_rcp_f32_e32 v53, v52
	s_nop 0
	v_fma_f32 v56, -v52, v53, 1.0
	v_fmac_f32_e32 v53, v56, v53
	v_div_scale_f32 v56, vcc, v54, v39, v54
	v_mul_f32_e32 v57, v56, v53
	v_fma_f32 v58, -v52, v57, v56
	v_fmac_f32_e32 v57, v58, v53
	v_fma_f32 v52, -v52, v57, v56
	v_div_fmas_f32 v52, v52, v53, v57
	v_div_fixup_f32 v39, v52, v39, v54
	v_div_scale_f32 v52, s[6:7], v38, v38, v55
	v_rcp_f32_e32 v53, v52
	s_nop 0
	v_fma_f32 v54, -v52, v53, 1.0
	v_fmac_f32_e32 v53, v54, v53
	v_div_scale_f32 v54, vcc, v55, v38, v55
	v_mul_f32_e32 v56, v54, v53
	v_fma_f32 v57, -v52, v56, v54
	v_fmac_f32_e32 v56, v57, v53
	v_fma_f32 v52, -v52, v56, v54
	v_div_fmas_f32 v52, v52, v53, v56
	v_div_fixup_f32 v38, v52, v38, v55
	v_mov_b32_e32 v52, v41
	v_mov_b32_e32 v53, v43
	v_pk_add_f32 v[48:49], v[52:53], v[48:49]
	v_mov_b32_e32 v41, v42
	v_pk_add_f32 v[40:41], v[40:41], v[48:49]
	v_mov_b32_e32 v42, v51
	v_mov_b32_e32 v43, v47
	v_pk_add_f32 v[40:41], v[42:43], v[40:41]
	v_mov_b32_e32 v51, v46
	v_pk_add_f32 v[40:41], v[50:51], v[40:41]
	s_nop 1
	v_mov_b32_dpp v43, v41 quad_perm:[1,0,3,2] row_mask:0xf bank_mask:0xf bound_ctrl:1
	v_mov_b32_dpp v42, v40 quad_perm:[1,0,3,2] row_mask:0xf bank_mask:0xf bound_ctrl:1
	v_pk_add_f32 v[40:41], v[40:41], v[42:43]
	s_nop 1
	v_mov_b32_dpp v43, v41 quad_perm:[2,3,0,1] row_mask:0xf bank_mask:0xf bound_ctrl:1
	v_mov_b32_dpp v42, v40 quad_perm:[2,3,0,1] row_mask:0xf bank_mask:0xf bound_ctrl:1
	v_pk_add_f32 v[40:41], v[40:41], v[42:43]
	s_nop 1
	v_mov_b32_dpp v43, v41 row_half_mirror row_mask:0xf bank_mask:0xf bound_ctrl:1
	v_mov_b32_dpp v42, v40 row_half_mirror row_mask:0xf bank_mask:0xf bound_ctrl:1
	v_pk_add_f32 v[40:41], v[40:41], v[42:43]
	s_nop 1
	v_mov_b32_dpp v43, v41 row_mirror row_mask:0xf bank_mask:0xf bound_ctrl:1
	v_mov_b32_dpp v42, v40 row_mirror row_mask:0xf bank_mask:0xf bound_ctrl:1
	v_pk_add_f32 v[40:41], v[40:41], v[42:43]
	ds_bpermute_b32 v43, v44, v41
	ds_bpermute_b32 v42, v44, v40
	s_waitcnt lgkmcnt(0)
; DI uint4 pack8(const float* f) { uint4 o; o.x = pk2(f[0], f[1]); o.y = pk2(f[2], f[3]); o.z = pk2(f[4], f[5]); o.w = pk2(f[6], f[7]); return o; }
; DI float sum16(float v) { v = sum8(v); v += dpp_f<0x140>(v); return v; }
; DI float silu_f(float g) { return g / (1.0f + __expf(-g)); }
; DI void phase_ret_merge(PrmC p, int nrows, int gw, int NGW) {
;     ...
;         for (int g = 0; g < 4; ++g) {
;             const size_t off = (size_t)row * 2048 + g * 512 + lane * 8;
;             float a[8], c[8], z[8]; unpack8(ra[g], a); unpack8(rc[g], c); unpack8(rz[g], z);
;             float ss = 0.f;
; #pragma unroll
;             for (int e = 0; e < 8; ++e) { a[e] += c[e]; ss += a[e] * a[e]; }
;             ss = sum16(ss); ss += __shfl_xor(ss, 16);
;             const float rstd = rsqrtf(ss * (1.0f / 256.0f) + 1e-6f);
; #pragma unroll
;             for (int e = 0; e < 8; ++e) a[e] = a[e] * rstd * silu_f(z[e]);
;             *(uint4*)(row < T_LAT ? Y + off : Y + (size_t)T_LAT * 2048 + ((size_t)(g >> 1) * 2048 + (row - T_LAT)) * 1024 + (g & 1) * 512 + lane * 8) = pack8(a);
	v_pk_add_f32 v[40:41], v[40:41], v[42:43]
	v_mov_b64_e32 v[42:43], s[30:31]
	v_pk_fma_f32 v[40:41], v[40:41], s[28:29], v[42:43] op_sel_hi:[1,0,0]
	s_nop 0
	v_mul_f32_e32 v46, 0x4b800000, v41
	v_cmp_gt_f32_e64 s[6:7], s70, v41
	v_cmp_gt_f32_e32 vcc, s70, v40
	s_nop 0
	v_cndmask_b32_e64 v41, v41, v46, s[6:7]
	v_rsq_f32_e32 v41, v41
	s_nop 0
	v_mul_f32_e32 v46, 0x45800000, v41
	v_cndmask_b32_e64 v46, v41, v46, s[6:7]
	v_pk_mul_f32 v[4:5], v[4:5], v[46:47] op_sel_hi:[1,0]
	v_pk_mul_f32 v[2:3], v[2:3], v[46:47] op_sel_hi:[1,0]
	v_pk_mul_f32 v[4:5], v[6:7], v[4:5]
	v_pk_mul_f32 v[2:3], v[8:9], v[2:3]
	v_pk_mul_f32 v[8:9], v[16:17], v[46:47] op_sel_hi:[1,0]
	v_and_b32_sdwa v16, v5, v242 dst_sel:DWORD dst_unused:UNUSED_PAD src0_sel:WORD_1 src1_sel:DWORD
	v_and_b32_sdwa v17, v4, v242 dst_sel:DWORD dst_unused:UNUSED_PAD src0_sel:WORD_1 src1_sel:DWORD
	v_add3_u32 v4, v4, v17, s71
	v_add3_u32 v5, v5, v16, s71
	v_and_b32_sdwa v16, v3, v242 dst_sel:DWORD dst_unused:UNUSED_PAD src0_sel:WORD_1 src1_sel:DWORD
	v_and_b32_sdwa v17, v2, v242 dst_sel:DWORD dst_unused:UNUSED_PAD src0_sel:WORD_1 src1_sel:DWORD
	v_pk_mul_f32 v[6:7], v[18:19], v[46:47] op_sel_hi:[1,0]
	v_add3_u32 v3, v3, v16, s71
	v_add3_u32 v2, v2, v17, s71
	v_pk_mul_f32 v[6:7], v[20:21], v[6:7]
	v_and_b32_e32 v3, 0xffff0000, v3
	v_and_b32_e32 v2, 0xffff0000, v2
	v_pk_mul_f32 v[8:9], v[26:27], v[8:9]
	v_or_b32_sdwa v3, v3, v5 dst_sel:DWORD dst_unused:UNUSED_PAD src0_sel:DWORD src1_sel:WORD_1
	v_or_b32_sdwa v2, v2, v4 dst_sel:DWORD dst_unused:UNUSED_PAD src0_sel:DWORD src1_sel:WORD_1
	v_and_b32_sdwa v4, v7, v242 dst_sel:DWORD dst_unused:UNUSED_PAD src0_sel:WORD_1 src1_sel:DWORD
	v_and_b32_sdwa v5, v6, v242 dst_sel:DWORD dst_unused:UNUSED_PAD src0_sel:WORD_1 src1_sel:DWORD
	v_add3_u32 v6, v6, v5, s71
	v_add3_u32 v4, v7, v4, s71
	v_and_b32_sdwa v5, v9, v242 dst_sel:DWORD dst_unused:UNUSED_PAD src0_sel:WORD_1 src1_sel:DWORD
	v_and_b32_sdwa v7, v8, v242 dst_sel:DWORD dst_unused:UNUSED_PAD src0_sel:WORD_1 src1_sel:DWORD
	v_add3_u32 v5, v9, v5, s71
	v_add3_u32 v7, v8, v7, s71
	v_and_b32_e32 v5, 0xffff0000, v5
	v_and_b32_e32 v7, 0xffff0000, v7
	v_or_b32_sdwa v5, v5, v4 dst_sel:DWORD dst_unused:UNUSED_PAD src0_sel:DWORD src1_sel:WORD_1
	v_or_b32_sdwa v4, v7, v6 dst_sel:DWORD dst_unused:UNUSED_PAD src0_sel:DWORD src1_sel:WORD_1
	v_mul_f32_e32 v6, 0x4b800000, v40
	v_cndmask_b32_e32 v6, v40, v6, vcc
	v_rsq_f32_e32 v6, v6
	s_nop 0
	v_mul_f32_e32 v7, 0x45800000, v6
	v_cndmask_b32_e32 v6, v6, v7, vcc
	v_pk_mul_f32 v[8:9], v[24:25], v[6:7] op_sel_hi:[1,0]
	v_pk_mul_f32 v[16:17], v[22:23], v[6:7] op_sel_hi:[1,0]
	v_pk_mul_f32 v[8:9], v[28:29], v[8:9]
	v_pk_mul_f32 v[16:17], v[30:31], v[16:17]
	v_pk_mul_f32 v[18:19], v[34:35], v[6:7] op_sel_hi:[1,0]
	v_pk_mul_f32 v[6:7], v[32:33], v[6:7] op_sel_hi:[1,0]
	s_waitcnt vmcnt(3)
	v_mov_b64_e32 v[22:23], v[76:77]
	v_mov_b64_e32 v[24:25], v[78:79]
	v_mov_b64_e32 v[26:27], v[80:81]
	v_mov_b64_e32 v[28:29], v[82:83]
	v_mov_b64_e32 v[30:31], v[84:85]
	v_mov_b64_e32 v[32:33], v[86:87]
	v_pk_mul_f32 v[20:21], v[38:39], v[6:7]
	v_and_b32_sdwa v6, v9, v242 dst_sel:DWORD dst_unused:UNUSED_PAD src0_sel:WORD_1 src1_sel:DWORD
	v_and_b32_sdwa v7, v8, v242 dst_sel:DWORD dst_unused:UNUSED_PAD src0_sel:WORD_1 src1_sel:DWORD
	v_add3_u32 v8, v8, v7, s71
	v_add3_u32 v6, v9, v6, s71
	v_and_b32_sdwa v7, v17, v242 dst_sel:DWORD dst_unused:UNUSED_PAD src0_sel:WORD_1 src1_sel:DWORD
	v_and_b32_sdwa v9, v16, v242 dst_sel:DWORD dst_unused:UNUSED_PAD src0_sel:WORD_1 src1_sel:DWORD
	v_add3_u32 v7, v17, v7, s71
	v_add3_u32 v9, v16, v9, s71
	v_pk_mul_f32 v[18:19], v[36:37], v[18:19]
	v_and_b32_e32 v7, 0xffff0000, v7
	v_and_b32_e32 v9, 0xffff0000, v9
	v_or_b32_sdwa v7, v7, v6 dst_sel:DWORD dst_unused:UNUSED_PAD src0_sel:DWORD src1_sel:WORD_1
	v_or_b32_sdwa v6, v9, v8 dst_sel:DWORD dst_unused:UNUSED_PAD src0_sel:DWORD src1_sel:WORD_1
	v_and_b32_sdwa v9, v18, v242 dst_sel:DWORD dst_unused:UNUSED_PAD src0_sel:WORD_1 src1_sel:DWORD
	v_add3_u32 v16, v18, v9, s71
	v_and_b32_sdwa v9, v21, v242 dst_sel:DWORD dst_unused:UNUSED_PAD src0_sel:WORD_1 src1_sel:DWORD
	v_and_b32_sdwa v17, v20, v242 dst_sel:DWORD dst_unused:UNUSED_PAD src0_sel:WORD_1 src1_sel:DWORD
	v_and_b32_sdwa v8, v19, v242 dst_sel:DWORD dst_unused:UNUSED_PAD src0_sel:WORD_1 src1_sel:DWORD
	v_add3_u32 v9, v21, v9, s71
	v_add3_u32 v17, v20, v17, s71
	v_add3_u32 v8, v19, v8, s71
	v_and_b32_e32 v9, 0xffff0000, v9
	v_and_b32_e32 v17, 0xffff0000, v17
	v_or_b32_sdwa v9, v9, v8 dst_sel:DWORD dst_unused:UNUSED_PAD src0_sel:DWORD src1_sel:WORD_1
	v_or_b32_sdwa v8, v17, v16 dst_sel:DWORD dst_unused:UNUSED_PAD src0_sel:DWORD src1_sel:WORD_1
	v_lshlrev_b32_e32 v17, 16, v23
	v_lshlrev_b32_e32 v16, 16, v22
	v_and_b32_e32 v21, 0xffff0000, v23
	v_and_b32_e32 v20, 0xffff0000, v22
	v_lshlrev_b32_e32 v19, 16, v27
	v_lshlrev_b32_e32 v18, 16, v26
	v_and_b32_e32 v23, 0xffff0000, v27
	v_and_b32_e32 v22, 0xffff0000, v26
	v_pk_add_f32 v[18:19], v[16:17], v[18:19]
	v_pk_add_f32 v[16:17], v[20:21], v[22:23]
	v_lshlrev_b32_e32 v27, 16, v30
	v_and_b32_e32 v30, 0xffff0000, v30
	v_mov_b32_e32 v20, v17
	v_mov_b32_e32 v21, v19
	v_lshlrev_b32_e32 v26, 16, v31
	v_pk_mul_f32 v[36:37], v[20:21], v[20:21]
	v_mul_f32_e32 v21, 0xbfb8aa3b, v30
	v_mul_f32_e32 v20, 0xbfb8aa3b, v27
	v_exp_f32_e32 v22, v21
	v_mul_f32_e32 v21, 0xbfb8aa3b, v26
	v_exp_f32_e32 v20, v20
	v_exp_f32_e32 v21, v21
	v_and_b32_e32 v31, 0xffff0000, v31
	v_and_b32_e32 v40, 0xffff0000, v32
	v_pk_add_f32 v[20:21], v[20:21], 1.0 op_sel_hi:[1,0]
	s_nop 0
	v_div_scale_f32 v23, s[6:7], v21, v21, v26
	v_rcp_f32_e32 v34, v23
	s_nop 0
	v_fma_f32 v35, -v23, v34, 1.0
	v_fmac_f32_e32 v34, v35, v34
	v_div_scale_f32 v35, vcc, v26, v21, v26
; DI uint4 pack8(const float* f) { uint4 o; o.x = pk2(f[0], f[1]); o.y = pk2(f[2], f[3]); o.z = pk2(f[4], f[5]); o.w = pk2(f[6], f[7]); return o; }
; DI float sum16(float v) { v = sum8(v); v += dpp_f<0x140>(v); return v; }
; DI float silu_f(float g) { return g / (1.0f + __expf(-g)); }
; DI void phase_ret_merge(PrmC p, int nrows, int gw, int NGW) {
;     ...
;         for (int g = 0; g < 4; ++g) { const size_t off = (size_t)row * 2048 + g * 512 + lane * 8;
;             ra[g] = *(const uint4*)(ORp + off); rc[g] = *(const uint4*)(ORp + (size_t)T_ALL * 2048 + off); rz[g] = *(const uint4*)(PG + off); }
; #pragma unroll
;         for (int g = 0; g < 4; ++g) {
;             const size_t off = (size_t)row * 2048 + g * 512 + lane * 8;
;             float a[8], c[8], z[8]; unpack8(ra[g], a); unpack8(rc[g], c); unpack8(rz[g], z);
;             float ss = 0.f;
; #pragma unroll
;             for (int e = 0; e < 8; ++e) { a[e] += c[e]; ss += a[e] * a[e]; }
;             ss = sum16(ss); ss += __shfl_xor(ss, 16);
;             const float rstd = rsqrtf(ss * (1.0f / 256.0f) + 1e-6f);
; #pragma unroll
;             for (int e = 0; e < 8; ++e) a[e] = a[e] * rstd * silu_f(z[e]);
;             *(uint4*)(row < T_LAT ? Y + off : Y + (size_t)T_LAT * 2048 + ((size_t)(g >> 1) * 2048 + (row - T_LAT)) * 1024 + (g & 1) * 512 + lane * 8) = pack8(a);
	v_mul_f32_e32 v38, v35, v34
	v_fma_f32 v39, -v23, v38, v35
	v_fmac_f32_e32 v38, v39, v34
	v_fma_f32 v23, -v23, v38, v35
	v_div_fmas_f32 v23, v23, v34, v38
	v_div_fixup_f32 v21, v23, v21, v26
	v_div_scale_f32 v23, s[6:7], v20, v20, v27
	v_rcp_f32_e32 v26, v23
	v_and_b32_e32 v39, 0xffff0000, v33
	v_fma_f32 v34, -v23, v26, 1.0
	v_fmac_f32_e32 v26, v34, v26
	v_div_scale_f32 v34, vcc, v27, v20, v27
	v_mul_f32_e32 v35, v34, v26
	v_fma_f32 v38, -v23, v35, v34
	v_fmac_f32_e32 v35, v38, v26
	v_fma_f32 v23, -v23, v35, v34
	v_div_fmas_f32 v23, v23, v26, v35
	v_div_fixup_f32 v20, v23, v20, v27
	v_mul_f32_e32 v23, 0xbfb8aa3b, v31
	v_exp_f32_e32 v23, v23
	s_nop 0
	v_pk_add_f32 v[22:23], v[22:23], 1.0 op_sel_hi:[1,0]
	s_nop 0
	v_div_scale_f32 v26, s[6:7], v23, v23, v31
	v_rcp_f32_e32 v27, v26
	s_nop 0
	v_fma_f32 v34, -v26, v27, 1.0
	v_fmac_f32_e32 v27, v34, v27
	v_div_scale_f32 v34, vcc, v31, v23, v31
	v_mul_f32_e32 v35, v34, v27
	v_fma_f32 v38, -v26, v35, v34
	v_fmac_f32_e32 v35, v38, v27
	v_fma_f32 v26, -v26, v35, v34
	v_div_fmas_f32 v26, v26, v27, v35
	v_div_fixup_f32 v23, v26, v23, v31
	v_div_scale_f32 v26, s[6:7], v22, v22, v30
	v_rcp_f32_e32 v27, v26
	v_lshlrev_b32_e32 v38, 16, v32
	v_fma_f32 v31, -v26, v27, 1.0
	v_fmac_f32_e32 v27, v31, v27
	v_div_scale_f32 v31, vcc, v30, v22, v30
	v_mul_f32_e32 v34, v31, v27
	v_fma_f32 v35, -v26, v34, v31
	v_fmac_f32_e32 v34, v35, v27
	v_fma_f32 v26, -v26, v34, v31
	v_div_fmas_f32 v26, v26, v27, v34
	v_div_fixup_f32 v22, v26, v22, v30
	v_lshlrev_b32_e32 v27, 16, v25
	v_lshlrev_b32_e32 v26, 16, v24
	v_and_b32_e32 v25, 0xffff0000, v25
	v_and_b32_e32 v24, 0xffff0000, v24
	v_lshlrev_b32_e32 v31, 16, v29
	v_lshlrev_b32_e32 v30, 16, v28
	v_and_b32_e32 v29, 0xffff0000, v29
	v_and_b32_e32 v28, 0xffff0000, v28
	v_pk_add_f32 v[26:27], v[26:27], v[30:31]
	v_pk_add_f32 v[24:25], v[24:25], v[28:29]
	v_mov_b32_e32 v29, v26
	v_mov_b32_e32 v28, v24
	v_lshlrev_b32_e32 v35, 16, v33
	v_pk_mul_f32 v[32:33], v[28:29], v[28:29]
	v_mov_b32_e32 v28, v25
	v_mov_b32_e32 v29, v27
	v_pk_mul_f32 v[30:31], v[28:29], v[28:29]
	v_mul_f32_e32 v29, 0xbfb8aa3b, v40
	v_mul_f32_e32 v28, 0xbfb8aa3b, v38
	v_exp_f32_e32 v34, v29
	v_mul_f32_e32 v29, 0xbfb8aa3b, v35
	v_exp_f32_e32 v28, v28
	v_exp_f32_e32 v29, v29
	s_nop 0
	v_pk_add_f32 v[28:29], v[28:29], 1.0 op_sel_hi:[1,0]
	s_nop 0
	v_div_scale_f32 v41, s[6:7], v29, v29, v35
	v_rcp_f32_e32 v46, v41
	s_nop 0
	v_fma_f32 v47, -v41, v46, 1.0
	v_fmac_f32_e32 v46, v47, v46
	v_div_scale_f32 v47, vcc, v35, v29, v35
	v_mul_f32_e32 v48, v47, v46
	v_fma_f32 v49, -v41, v48, v47
	v_fmac_f32_e32 v48, v49, v46
	v_fma_f32 v41, -v41, v48, v47
	v_div_fmas_f32 v41, v41, v46, v48
	v_div_fixup_f32 v29, v41, v29, v35
	v_div_scale_f32 v35, s[6:7], v28, v28, v38
	v_rcp_f32_e32 v41, v35
	s_nop 0
	v_fma_f32 v46, -v35, v41, 1.0
	v_fmac_f32_e32 v41, v46, v41
	v_div_scale_f32 v46, vcc, v38, v28, v38
	v_mul_f32_e32 v47, v46, v41
	v_fma_f32 v48, -v35, v47, v46
	v_fmac_f32_e32 v47, v48, v41
	v_fma_f32 v35, -v35, v47, v46
	v_div_fmas_f32 v35, v35, v41, v47
	v_div_fixup_f32 v28, v35, v28, v38
	v_mul_f32_e32 v35, 0xbfb8aa3b, v39
	v_exp_f32_e32 v35, v35
	s_nop 0
	v_pk_add_f32 v[34:35], v[34:35], 1.0 op_sel_hi:[1,0]
	s_nop 0
	v_div_scale_f32 v38, s[6:7], v35, v35, v39
	v_rcp_f32_e32 v41, v38
	s_nop 0
	v_fma_f32 v46, -v38, v41, 1.0
	v_fmac_f32_e32 v41, v46, v41
	v_div_scale_f32 v46, vcc, v39, v35, v39
	v_mul_f32_e32 v47, v46, v41
	v_fma_f32 v48, -v38, v47, v46
	v_fmac_f32_e32 v47, v48, v41
	v_fma_f32 v38, -v38, v47, v46
	v_div_fmas_f32 v38, v38, v41, v47
	v_div_fixup_f32 v35, v38, v35, v39
	v_div_scale_f32 v38, s[6:7], v34, v34, v40
	v_rcp_f32_e32 v39, v38
	s_nop 0
	v_fma_f32 v41, -v38, v39, 1.0
	v_fmac_f32_e32 v39, v41, v39
	v_div_scale_f32 v41, vcc, v40, v34, v40
	v_mul_f32_e32 v46, v41, v39
	v_fma_f32 v47, -v38, v46, v41
	v_fmac_f32_e32 v46, v47, v39
	v_fma_f32 v38, -v38, v46, v41
	v_div_fmas_f32 v38, v38, v39, v46
	v_div_fixup_f32 v34, v38, v34, v40
	s_waitcnt vmcnt(0)
	v_mov_b64_e32 v[38:39], v[88:89]
	v_mov_b64_e32 v[40:41], v[90:91]
	s_nop 0
	v_mov_b64_e32 v[10:11], v[92:93]
	v_mov_b64_e32 v[12:13], v[94:95]
	s_nop 0
	v_mov_b64_e32 v[46:47], v[96:97]
	v_mov_b64_e32 v[48:49], v[98:99]
	s_nop 0
	global_store_dwordx4 v45, v[2:5], s[12:13]
	global_store_dwordx4 v45, v[6:9], s[12:13] offset:1024
	s_nop 1
	v_lshlrev_b32_e32 v15, 16, v39
	v_lshlrev_b32_e32 v14, 16, v38
	v_and_b32_e32 v39, 0xffff0000, v39
	v_and_b32_e32 v38, 0xffff0000, v38
	v_lshlrev_b32_e32 v51, 16, v11
	v_lshlrev_b32_e32 v50, 16, v10
	v_and_b32_e32 v11, 0xffff0000, v11
	v_and_b32_e32 v10, 0xffff0000, v10
	v_pk_add_f32 v[14:15], v[14:15], v[50:51]
	v_pk_add_f32 v[10:11], v[38:39], v[10:11]
	v_mov_b32_e32 v39, v15
	v_mov_b32_e32 v38, v11
	v_mov_b32_e32 v50, v10
	v_mov_b32_e32 v51, v16
	v_lshlrev_b32_e32 v52, 16, v47
	v_lshlrev_b32_e32 v53, 16, v46
	v_and_b32_e32 v54, 0xffff0000, v47
	v_and_b32_e32 v55, 0xffff0000, v46
	v_pk_mul_f32 v[38:39], v[38:39], v[38:39]
	v_mov_b32_e32 v46, v14
	v_mov_b32_e32 v47, v18
	v_pk_mul_f32 v[50:51], v[50:51], v[50:51]
	v_and_b32_e32 v58, 0xffff0000, v48
	v_pk_fma_f32 v[46:47], v[46:47], v[46:47], v[50:51]
	v_mov_b32_e32 v50, v39
	v_mov_b32_e32 v51, v37
	v_pk_add_f32 v[46:47], v[46:47], v[50:51]
	v_mov_b32_e32 v39, v36
	v_pk_add_f32 v[36:37], v[38:39], v[46:47]
	v_mul_f32_e32 v39, 0xbfb8aa3b, v55
	v_mul_f32_e32 v38, 0xbfb8aa3b, v53
	v_exp_f32_e32 v46, v39
	v_mul_f32_e32 v39, 0xbfb8aa3b, v52
	v_exp_f32_e32 v38, v38
	v_exp_f32_e32 v39, v39
	v_mov_b32_e32 v3, v33
	v_mov_b32_e32 v5, v31
	v_pk_add_f32 v[38:39], v[38:39], 1.0 op_sel_hi:[1,0]
	s_nop 0
	v_div_scale_f32 v47, s[6:7], v39, v39, v52
	v_rcp_f32_e32 v50, v47
	s_nop 0
	v_fma_f32 v51, -v47, v50, 1.0
; DI float sum16(float v) { v = sum8(v); v += dpp_f<0x140>(v); return v; }
; DI float silu_f(float g) { return g / (1.0f + __expf(-g)); }
; DI void phase_ret_merge(PrmC p, int nrows, int gw, int NGW) {
;     ...
;             float a[8], c[8], z[8]; unpack8(ra[g], a); unpack8(rc[g], c); unpack8(rz[g], z);
;             float ss = 0.f;
; #pragma unroll
;             for (int e = 0; e < 8; ++e) { a[e] += c[e]; ss += a[e] * a[e]; }
;             ss = sum16(ss); ss += __shfl_xor(ss, 16);
;             const float rstd = rsqrtf(ss * (1.0f / 256.0f) + 1e-6f);
; #pragma unroll
;             for (int e = 0; e < 8; ++e) a[e] = a[e] * rstd * silu_f(z[e]);
	v_fmac_f32_e32 v50, v51, v50
	v_div_scale_f32 v51, vcc, v52, v39, v52
	v_mul_f32_e32 v56, v51, v50
	v_fma_f32 v57, -v47, v56, v51
	v_fmac_f32_e32 v56, v57, v50
	v_fma_f32 v47, -v47, v56, v51
	v_div_fmas_f32 v47, v47, v50, v56
	v_div_fixup_f32 v39, v47, v39, v52
	v_div_scale_f32 v47, s[6:7], v38, v38, v53
	v_rcp_f32_e32 v50, v47
	v_and_b32_e32 v57, 0xffff0000, v49
	v_fma_f32 v51, -v47, v50, 1.0
	v_fmac_f32_e32 v50, v51, v50
	v_div_scale_f32 v51, vcc, v53, v38, v53
	v_mul_f32_e32 v52, v51, v50
	v_fma_f32 v56, -v47, v52, v51
	v_fmac_f32_e32 v52, v56, v50
	v_fma_f32 v47, -v47, v52, v51
	v_div_fmas_f32 v47, v47, v50, v52
	v_div_fixup_f32 v38, v47, v38, v53
	v_mul_f32_e32 v47, 0xbfb8aa3b, v54
	v_exp_f32_e32 v47, v47
	s_nop 0
	v_pk_add_f32 v[46:47], v[46:47], 1.0 op_sel_hi:[1,0]
	s_nop 0
	v_div_scale_f32 v50, s[6:7], v47, v47, v54
	v_rcp_f32_e32 v51, v50
	s_nop 0
	v_fma_f32 v52, -v50, v51, 1.0
	v_fmac_f32_e32 v51, v52, v51
	v_div_scale_f32 v52, vcc, v54, v47, v54
	v_mul_f32_e32 v53, v52, v51
	v_fma_f32 v56, -v50, v53, v52
	v_fmac_f32_e32 v53, v56, v51
	v_fma_f32 v50, -v50, v53, v52
	v_div_fmas_f32 v50, v50, v51, v53
	v_div_fixup_f32 v47, v50, v47, v54
	v_div_scale_f32 v50, s[6:7], v46, v46, v55
	v_rcp_f32_e32 v51, v50
	v_lshlrev_b32_e32 v56, 16, v48
	v_fma_f32 v52, -v50, v51, 1.0
	v_fmac_f32_e32 v51, v52, v51
	v_div_scale_f32 v52, vcc, v55, v46, v55
	v_mul_f32_e32 v53, v52, v51
	v_fma_f32 v54, -v50, v53, v52
	v_fmac_f32_e32 v53, v54, v51
	v_fma_f32 v50, -v50, v53, v52
	v_div_fmas_f32 v50, v50, v51, v53
	v_div_fixup_f32 v46, v50, v46, v55
	v_lshlrev_b32_e32 v51, 16, v41
	v_lshlrev_b32_e32 v50, 16, v40
	v_lshlrev_b32_e32 v53, 16, v13
	v_lshlrev_b32_e32 v52, 16, v12
	v_lshlrev_b32_e32 v55, 16, v49
	v_pk_add_f32 v[48:49], v[50:51], v[52:53]
	v_mul_f32_e32 v53, 0xbfb8aa3b, v58
	v_mul_f32_e32 v52, 0xbfb8aa3b, v56
	v_exp_f32_e32 v54, v53
	v_mul_f32_e32 v53, 0xbfb8aa3b, v55
	v_exp_f32_e32 v52, v52
	v_exp_f32_e32 v53, v53
	v_and_b32_e32 v41, 0xffff0000, v41
	v_and_b32_e32 v40, 0xffff0000, v40
	v_and_b32_e32 v13, 0xffff0000, v13
	v_pk_add_f32 v[52:53], v[52:53], 1.0 op_sel_hi:[1,0]
	v_and_b32_e32 v12, 0xffff0000, v12
	v_div_scale_f32 v59, s[6:7], v53, v53, v55
	v_rcp_f32_e32 v60, v59
	v_pk_add_f32 v[12:13], v[40:41], v[12:13]
	v_mov_b32_e32 v41, v48
	v_mov_b32_e32 v40, v12
	v_fma_f32 v61, -v59, v60, 1.0
	v_fmac_f32_e32 v60, v61, v60
	v_div_scale_f32 v61, vcc, v55, v53, v55
	v_mul_f32_e32 v62, v61, v60
	v_fma_f32 v63, -v59, v62, v61
	v_fmac_f32_e32 v62, v63, v60
	v_fma_f32 v59, -v59, v62, v61
	v_div_fmas_f32 v59, v59, v60, v62
	v_div_fixup_f32 v53, v59, v53, v55
	v_div_scale_f32 v55, s[6:7], v52, v52, v56
	v_rcp_f32_e32 v59, v55
	v_pk_mul_f32 v[40:41], v[40:41], v[40:41]
	v_mov_b32_e32 v50, v13
	v_mov_b32_e32 v51, v49
	v_fma_f32 v60, -v55, v59, 1.0
	v_fmac_f32_e32 v59, v60, v59
	v_div_scale_f32 v60, vcc, v56, v52, v56
	v_mul_f32_e32 v61, v60, v59
	v_fma_f32 v62, -v55, v61, v60
	v_fmac_f32_e32 v61, v62, v59
	v_fma_f32 v55, -v55, v61, v60
	v_div_fmas_f32 v55, v55, v59, v61
	v_mov_b32_e32 v2, v41
	v_pk_mul_f32 v[50:51], v[50:51], v[50:51]
	v_div_fixup_f32 v52, v55, v52, v56
	v_mul_f32_e32 v55, 0xbfb8aa3b, v57
	v_pk_add_f32 v[2:3], v[2:3], v[36:37]
	v_mov_b32_e32 v41, v32
	v_exp_f32_e32 v55, v55
	v_pk_add_f32 v[2:3], v[40:41], v[2:3]
	v_mov_b32_e32 v4, v51
	v_pk_add_f32 v[2:3], v[4:5], v[2:3]
	v_mov_b32_e32 v51, v30
	v_pk_add_f32 v[2:3], v[50:51], v[2:3]
	v_pk_add_f32 v[54:55], v[54:55], 1.0 op_sel_hi:[1,0]
	s_nop 0
	v_mov_b32_dpp v5, v3 quad_perm:[1,0,3,2] row_mask:0xf bank_mask:0xf bound_ctrl:1
	v_mov_b32_dpp v4, v2 quad_perm:[1,0,3,2] row_mask:0xf bank_mask:0xf bound_ctrl:1
	v_pk_add_f32 v[2:3], v[2:3], v[4:5]
	v_div_scale_f32 v56, s[6:7], v55, v55, v57
	s_nop 0
	v_mov_b32_dpp v5, v3 quad_perm:[2,3,0,1] row_mask:0xf bank_mask:0xf bound_ctrl:1
	v_mov_b32_dpp v4, v2 quad_perm:[2,3,0,1] row_mask:0xf bank_mask:0xf bound_ctrl:1
	v_rcp_f32_e32 v59, v56
	v_pk_add_f32 v[2:3], v[2:3], v[4:5]
	v_fma_f32 v60, -v56, v59, 1.0
	s_nop 0
	v_mov_b32_dpp v5, v3 row_half_mirror row_mask:0xf bank_mask:0xf bound_ctrl:1
	v_mov_b32_dpp v4, v2 row_half_mirror row_mask:0xf bank_mask:0xf bound_ctrl:1
	v_pk_add_f32 v[2:3], v[2:3], v[4:5]
	v_fmac_f32_e32 v59, v60, v59
	v_div_scale_f32 v60, vcc, v57, v55, v57
	v_mov_b32_dpp v5, v3 row_mirror row_mask:0xf bank_mask:0xf bound_ctrl:1
	v_mov_b32_dpp v4, v2 row_mirror row_mask:0xf bank_mask:0xf bound_ctrl:1
	v_pk_add_f32 v[2:3], v[2:3], v[4:5]
	ds_bpermute_b32 v5, v44, v3
	ds_bpermute_b32 v4, v44, v2
	v_mul_f32_e32 v61, v60, v59
	v_fma_f32 v62, -v56, v61, v60
	v_fmac_f32_e32 v61, v62, v59
	v_fma_f32 v56, -v56, v61, v60
	v_div_fmas_f32 v56, v56, v59, v61
	s_waitcnt lgkmcnt(0)
; DI uint4 pack8(const float* f) { uint4 o; o.x = pk2(f[0], f[1]); o.y = pk2(f[2], f[3]); o.z = pk2(f[4], f[5]); o.w = pk2(f[6], f[7]); return o; }
; DI float silu_f(float g) { return g / (1.0f + __expf(-g)); }
; DI void phase_ret_merge(PrmC p, int nrows, int gw, int NGW) {
;     ...
;             const float rstd = rsqrtf(ss * (1.0f / 256.0f) + 1e-6f);
; #pragma unroll
;             for (int e = 0; e < 8; ++e) a[e] = a[e] * rstd * silu_f(z[e]);
;             *(uint4*)(row < T_LAT ? Y + off : Y + (size_t)T_LAT * 2048 + ((size_t)(g >> 1) * 2048 + (row - T_LAT)) * 1024 + (g & 1) * 512 + lane * 8) = pack8(a);
;         }
;     }
	v_pk_add_f32 v[2:3], v[2:3], v[4:5]
	v_div_fixup_f32 v55, v56, v55, v57
	v_div_scale_f32 v56, s[6:7], v54, v54, v58
	v_pk_fma_f32 v[6:7], v[2:3], s[28:29], v[42:43] op_sel_hi:[1,0,0]
	v_rcp_f32_e32 v57, v56
	v_mul_f32_e32 v2, 0x4b800000, v7
	v_cmp_gt_f32_e64 s[6:7], s70, v7
	v_fma_f32 v59, -v56, v57, 1.0
	s_nop 0
	v_cndmask_b32_e64 v2, v7, v2, s[6:7]
	v_rsq_f32_e32 v2, v2
	v_fmac_f32_e32 v57, v59, v57
	v_div_scale_f32 v59, vcc, v58, v54, v58
	v_mul_f32_e32 v3, 0x45800000, v2
	v_cndmask_b32_e64 v2, v2, v3, s[6:7]
	v_pk_mul_f32 v[4:5], v[18:19], v[2:3] op_sel_hi:[1,0]
	v_pk_mul_f32 v[8:9], v[16:17], v[2:3] op_sel_hi:[1,0]
	v_pk_mul_f32 v[4:5], v[20:21], v[4:5]
	v_pk_mul_f32 v[16:17], v[26:27], v[2:3] op_sel_hi:[1,0]
	v_pk_mul_f32 v[2:3], v[24:25], v[2:3] op_sel_hi:[1,0]
	v_pk_mul_f32 v[8:9], v[22:23], v[8:9]
	v_pk_mul_f32 v[18:19], v[34:35], v[2:3]
	v_and_b32_sdwa v2, v5, v242 dst_sel:DWORD dst_unused:UNUSED_PAD src0_sel:WORD_1 src1_sel:DWORD
	v_and_b32_sdwa v3, v4, v242 dst_sel:DWORD dst_unused:UNUSED_PAD src0_sel:WORD_1 src1_sel:DWORD
	v_add3_u32 v4, v4, v3, s71
	v_add3_u32 v2, v5, v2, s71
	v_and_b32_sdwa v3, v9, v242 dst_sel:DWORD dst_unused:UNUSED_PAD src0_sel:WORD_1 src1_sel:DWORD
	v_and_b32_sdwa v5, v8, v242 dst_sel:DWORD dst_unused:UNUSED_PAD src0_sel:WORD_1 src1_sel:DWORD
	v_add3_u32 v3, v9, v3, s71
	v_add3_u32 v5, v8, v5, s71
	v_pk_mul_f32 v[16:17], v[28:29], v[16:17]
	v_and_b32_e32 v3, 0xffff0000, v3
	v_and_b32_e32 v5, 0xffff0000, v5
	v_or_b32_sdwa v3, v3, v2 dst_sel:DWORD dst_unused:UNUSED_PAD src0_sel:DWORD src1_sel:WORD_1
	v_or_b32_sdwa v2, v5, v4 dst_sel:DWORD dst_unused:UNUSED_PAD src0_sel:DWORD src1_sel:WORD_1
	v_and_b32_sdwa v5, v16, v242 dst_sel:DWORD dst_unused:UNUSED_PAD src0_sel:WORD_1 src1_sel:DWORD
	v_mul_f32_e32 v60, v59, v57
	v_add3_u32 v7, v16, v5, s71
	v_and_b32_sdwa v5, v19, v242 dst_sel:DWORD dst_unused:UNUSED_PAD src0_sel:WORD_1 src1_sel:DWORD
	v_and_b32_sdwa v8, v18, v242 dst_sel:DWORD dst_unused:UNUSED_PAD src0_sel:WORD_1 src1_sel:DWORD
	v_fma_f32 v61, -v56, v60, v59
	v_and_b32_sdwa v4, v17, v242 dst_sel:DWORD dst_unused:UNUSED_PAD src0_sel:WORD_1 src1_sel:DWORD
	v_add3_u32 v5, v19, v5, s71
	v_add3_u32 v8, v18, v8, s71
	v_fmac_f32_e32 v60, v61, v57
	v_add3_u32 v4, v17, v4, s71
	v_and_b32_e32 v5, 0xffff0000, v5
	v_and_b32_e32 v8, 0xffff0000, v8
	v_fma_f32 v56, -v56, v60, v59
	v_or_b32_sdwa v5, v5, v4 dst_sel:DWORD dst_unused:UNUSED_PAD src0_sel:DWORD src1_sel:WORD_1
	v_or_b32_sdwa v4, v8, v7 dst_sel:DWORD dst_unused:UNUSED_PAD src0_sel:DWORD src1_sel:WORD_1
	v_div_fmas_f32 v56, v56, v57, v60
	v_cmp_gt_f32_e32 vcc, s70, v6
	global_store_dwordx4 v45, v[2:5], s[14:15]
	v_div_fixup_f32 v54, v56, v54, v58
	s_nop 0
	v_mul_f32_e32 v2, 0x4b800000, v6
	v_cndmask_b32_e32 v2, v6, v2, vcc
	v_rsq_f32_e32 v2, v2
	s_nop 0
	v_mul_f32_e32 v3, 0x45800000, v2
	v_cndmask_b32_e32 v2, v2, v3, vcc
	v_pk_mul_f32 v[4:5], v[14:15], v[2:3] op_sel_hi:[1,0]
	v_pk_mul_f32 v[6:7], v[10:11], v[2:3] op_sel_hi:[1,0]
	v_pk_mul_f32 v[4:5], v[38:39], v[4:5]
	v_pk_mul_f32 v[8:9], v[48:49], v[2:3] op_sel_hi:[1,0]
	v_pk_mul_f32 v[2:3], v[12:13], v[2:3] op_sel_hi:[1,0]
	v_pk_mul_f32 v[6:7], v[46:47], v[6:7]
	v_pk_mul_f32 v[10:11], v[54:55], v[2:3]
	v_and_b32_sdwa v2, v5, v242 dst_sel:DWORD dst_unused:UNUSED_PAD src0_sel:WORD_1 src1_sel:DWORD
	v_and_b32_sdwa v3, v4, v242 dst_sel:DWORD dst_unused:UNUSED_PAD src0_sel:WORD_1 src1_sel:DWORD
	v_add3_u32 v4, v4, v3, s71
	v_add3_u32 v2, v5, v2, s71
	v_and_b32_sdwa v3, v7, v242 dst_sel:DWORD dst_unused:UNUSED_PAD src0_sel:WORD_1 src1_sel:DWORD
	v_and_b32_sdwa v5, v6, v242 dst_sel:DWORD dst_unused:UNUSED_PAD src0_sel:WORD_1 src1_sel:DWORD
	v_add3_u32 v3, v7, v3, s71
	v_add3_u32 v5, v6, v5, s71
	v_pk_mul_f32 v[8:9], v[52:53], v[8:9]
	v_and_b32_e32 v3, 0xffff0000, v3
	v_and_b32_e32 v5, 0xffff0000, v5
	v_or_b32_sdwa v3, v3, v2 dst_sel:DWORD dst_unused:UNUSED_PAD src0_sel:DWORD src1_sel:WORD_1
	v_or_b32_sdwa v2, v5, v4 dst_sel:DWORD dst_unused:UNUSED_PAD src0_sel:DWORD src1_sel:WORD_1
	v_and_b32_sdwa v5, v8, v242 dst_sel:DWORD dst_unused:UNUSED_PAD src0_sel:WORD_1 src1_sel:DWORD
	v_add3_u32 v6, v8, v5, s71
	v_and_b32_sdwa v5, v11, v242 dst_sel:DWORD dst_unused:UNUSED_PAD src0_sel:WORD_1 src1_sel:DWORD
	v_and_b32_sdwa v7, v10, v242 dst_sel:DWORD dst_unused:UNUSED_PAD src0_sel:WORD_1 src1_sel:DWORD
	v_and_b32_sdwa v4, v9, v242 dst_sel:DWORD dst_unused:UNUSED_PAD src0_sel:WORD_1 src1_sel:DWORD
	v_add3_u32 v5, v11, v5, s71
	v_add3_u32 v7, v10, v7, s71
	v_add3_u32 v4, v9, v4, s71
	v_and_b32_e32 v5, 0xffff0000, v5
	v_and_b32_e32 v7, 0xffff0000, v7
	v_or_b32_sdwa v5, v5, v4 dst_sel:DWORD dst_unused:UNUSED_PAD src0_sel:DWORD src1_sel:WORD_1
	v_or_b32_sdwa v4, v7, v6 dst_sel:DWORD dst_unused:UNUSED_PAD src0_sel:DWORD src1_sel:WORD_1
	global_store_dwordx4 v45, v[2:5], s[16:17]
	s_cbranch_scc0 .LBB0_284

; DI void unpack8(const uint4 v, float* f) {
;     f[0] = __uint_as_float(v.x << 16); f[1] = __uint_as_float(v.x & 0xffff0000u); f[2] = __uint_as_float(v.y << 16); f[3] = __uint_as_float(v.y & 0xffff0000u);
;     f[4] = __uint_as_float(v.z << 16); f[5] = __uint_as_float(v.z & 0xffff0000u); f[6] = __uint_as_float(v.w << 16); f[7] = __uint_as_float(v.w & 0xffff0000u);
; }
; DI void phase_dn_chunkprep(PrmC p, unsigned char* smem, int vb, int nvb) {
;     ...
;         const int cidx = item % 36, bh = item / 36, h = bh & 3, b = bh >> 2;
;         const int row0 = cidx < 4 ? T_LAT + b * 256 + cidx * 64 : b * 2048 + (cidx - 4) * 64;
;         __syncthreads();
; #pragma unroll
;         for (int i = 0; i < 2; ++i) { const int idx = tid + i * NTHR, n = idx >> 4, seg = idx & 15; float kf[8], qf8[8];
;             const uint4 kraw = *(const uint4*)(KN + (size_t)(row0 + n) * 512 + h * 128 + seg * 8), qraw = *(const uint4*)(QN + (size_t)(row0 + n) * 512 + h * 128 + seg * 8);
;             unpack8(kraw, kf); unpack8(qraw, qf8);
;             *(__attribute__((address_space(3))) u32x4*)(Kb + n * 272 + seg * 16) = (u32x4){kraw.x, kraw.y, kraw.z, kraw.w}; *(__attribute__((address_space(3))) u32x4*)(Qb + n * 272 + seg * 16) = (u32x4){qraw.x, qraw.y, qraw.z, qraw.w};
;             *(float4*)(Kl + n * 132 + seg * 8) = make_float4(kf[0], kf[1], kf[2], kf[3]); *(float4*)(Kl + n * 132 + seg * 8 + 4) = make_float4(kf[4], kf[5], kf[6], kf[7]);
;             *(float4*)(Ql + n * 132 + seg * 8) = make_float4(qf8[0], qf8[1], qf8[2], qf8[3]); *(float4*)(Ql + n * 132 + seg * 8 + 4) = make_float4(qf8[4], qf8[5], qf8[6], qf8[7]); }
;         if (t < 64) {
;             const int n = d ? 63 - t : t;
;             float x = LA[(size_t)(row0 + n) * 8 + d * 4 + h];
; #pragma unroll
;             for (int o = 1; o < 64; o <<= 1) { const float y = __shfl_up(x, o); if (t >= o) x += y; }
;             Gn[d * 64 + n] = x; Bn[d * 64 + n] = BE[(size_t)(row0 + n) * 8 + d * 4 + h];
.LBB0_476:
	s_mul_hi_i32 s4, s38, 0x38e38e39
	s_lshr_b32 s20, s4, 31
	s_ashr_i32 s4, s4, 3
	s_add_i32 s20, s4, s20
	s_mul_i32 s4, s20, 0xffffffdc
	s_add_i32 s21, s38, s4
	s_and_b32 s4, s20, 3
	s_ashr_i32 s25, s20, 2
	s_cmp_lt_i32 s21, 4
	s_cselect_b32 s21, 8, 11
	s_movk_i32 s27, 0xff00
	s_cselect_b32 s27, 0x4000, s27
	s_lshl_b32 s21, s25, s21
	s_add_i32 s27, s27, s21
	s_mulk_i32 s20, 0x900
	s_sub_i32 s25, s27, s20
	s_add_i32 s25, s25, s37
	v_add_u32_e32 v2, s25, v111
	s_lshl_b32 s20, s4, 8
	s_mov_b32 s21, s36
	v_ashrrev_i32_e32 v3, 31, v2
	v_lshl_add_u64 v[30:31], v[18:19], 0, s[20:21]
	v_lshl_add_u64 v[32:33], v[20:21], 0, s[20:21]
	v_lshlrev_b64 v[6:7], 10, v[2:3]
	v_lshl_add_u64 v[2:3], v[30:31], 0, v[6:7]
	v_lshl_add_u64 v[6:7], v[32:33], 0, v[6:7]
	s_barrier
	s_mov_b64 s[20:21], exec
	s_and_b64 exec, exec, s[6:7]
	v_add_u32_e32 v236, s25, v108
	v_ashrrev_i32_e32 v237, 31, v236
	v_lshl_add_u64 v[236:237], v[236:237], 3, s[30:31]
	v_or_b32_e32 v236, s4, v236
	v_lshlrev_b64 v[236:237], 2, v[236:237]
	v_lshl_add_u64 v[228:229], s[54:55], 0, v[236:237]
	global_load_dword v234, v[228:229], off
	v_lshl_add_u64 v[236:237], s[68:69], 0, v[236:237]
	global_load_dword v235, v[236:237], off
	s_mov_b64 exec, s[20:21]
	global_load_dwordx4 v[2:5], v[2:3], off
	s_nop 0
	global_load_dwordx4 v[6:9], v[6:7], off
	v_add_u32_e32 v226, s25, v114
	v_ashrrev_i32_e32 v227, 31, v226
	v_lshlrev_b64 v[230:231], 10, v[226:227]
	v_lshl_add_u64 v[226:227], v[30:31], 0, v[230:231]
	v_lshl_add_u64 v[230:231], v[32:33], 0, v[230:231]
	global_load_dwordx4 v[226:229], v[226:227], off
	s_nop 0
	global_load_dwordx4 v[230:233], v[230:231], off
	s_waitcnt vmcnt(3)
	v_lshlrev_b32_e32 v10, 16, v2
	v_and_b32_e32 v11, 0xffff0000, v2
	v_lshlrev_b32_e32 v12, 16, v3
	v_and_b32_e32 v13, 0xffff0000, v3
	v_lshlrev_b32_e32 v14, 16, v4
	v_and_b32_e32 v15, 0xffff0000, v4
	v_lshlrev_b32_e32 v16, 16, v5
	v_and_b32_e32 v17, 0xffff0000, v5
	s_waitcnt vmcnt(2)
	v_lshlrev_b32_e32 v22, 16, v6
	v_and_b32_e32 v23, 0xffff0000, v6
	v_lshlrev_b32_e32 v24, 16, v7
	v_and_b32_e32 v25, 0xffff0000, v7
	v_lshlrev_b32_e32 v26, 16, v8
	v_and_b32_e32 v27, 0xffff0000, v8
	v_lshlrev_b32_e32 v28, 16, v9
	v_and_b32_e32 v29, 0xffff0000, v9
	ds_write_b128 v123, v[2:5]
	ds_write_b128 v123, v[6:9] offset:17408
	ds_write_b128 v112, v[10:13]
	ds_write_b128 v112, v[14:17] offset:16
	ds_write_b128 v113, v[22:25]
	ds_write_b128 v113, v[26:29] offset:16
	v_add_u32_e32 v2, s25, v114
	v_ashrrev_i32_e32 v3, 31, v2
	v_lshlrev_b64 v[6:7], 10, v[2:3]
	v_lshl_add_u64 v[2:3], v[30:31], 0, v[6:7]
	v_lshl_add_u64 v[6:7], v[32:33], 0, v[6:7]
	s_waitcnt vmcnt(1)
	v_mov_b64_e32 v[2:3], v[226:227]
	v_mov_b64_e32 v[4:5], v[228:229]
	s_nop 0
	s_waitcnt vmcnt(0)
	v_mov_b64_e32 v[6:7], v[230:231]
	v_mov_b64_e32 v[8:9], v[232:233]
	s_waitcnt vmcnt(1)
	v_lshlrev_b32_e32 v10, 16, v2
	v_and_b32_e32 v11, 0xffff0000, v2
	v_lshlrev_b32_e32 v12, 16, v3
	v_and_b32_e32 v13, 0xffff0000, v3
	v_lshlrev_b32_e32 v14, 16, v4
	v_and_b32_e32 v15, 0xffff0000, v4
	v_lshlrev_b32_e32 v16, 16, v5
	v_and_b32_e32 v17, 0xffff0000, v5
	s_waitcnt vmcnt(0)
	v_lshlrev_b32_e32 v22, 16, v6
	v_and_b32_e32 v23, 0xffff0000, v6
	v_lshlrev_b32_e32 v24, 16, v7
	v_and_b32_e32 v25, 0xffff0000, v7
	v_lshlrev_b32_e32 v26, 16, v8
	v_and_b32_e32 v27, 0xffff0000, v8
	v_lshlrev_b32_e32 v28, 16, v9
	v_and_b32_e32 v29, 0xffff0000, v9
	ds_write_b128 v124, v[2:5]
	ds_write_b128 v124, v[6:9] offset:17408
	ds_write_b128 v115, v[10:13]
	ds_write_b128 v115, v[14:17] offset:16
	ds_write_b128 v116, v[22:25]
	ds_write_b128 v116, v[26:29] offset:16
	s_and_saveexec_b64 s[20:21], s[6:7]
	s_cbranch_execz .LBB0_478
	v_add_u32_e32 v2, s25, v108
	v_ashrrev_i32_e32 v3, 31, v2
	v_lshl_add_u64 v[2:3], v[2:3], 3, s[30:31]
	v_or_b32_e32 v2, s4, v2
	v_lshlrev_b64 v[2:3], 2, v[2:3]
	v_lshl_add_u64 v[4:5], s[54:55], 0, v[2:3]
	v_mov_b32_e32 v0, v234
	v_lshl_add_u64 v[2:3], s[68:69], 0, v[2:3]
	v_mov_b32_e32 v2, v235
	v_readlane_b32 s28, v255, 22
	v_readlane_b32 s29, v255, 23
	s_waitcnt vmcnt(1)
	ds_bpermute_b32 v3, v117, v0
	s_waitcnt lgkmcnt(0)
	v_add_f32_e32 v3, v0, v3
	v_cndmask_b32_e64 v0, v3, v0, s[28:29]
	ds_bpermute_b32 v3, v118, v0
	v_readlane_b32 s28, v255, 24
	v_readlane_b32 s29, v255, 25
	s_waitcnt lgkmcnt(0)
	v_add_f32_e32 v3, v0, v3
	v_cndmask_b32_e64 v0, v3, v0, s[28:29]
	ds_bpermute_b32 v3, v119, v0
	v_readlane_b32 s28, v255, 26
	v_readlane_b32 s29, v255, 27
	s_waitcnt lgkmcnt(0)
	v_add_f32_e32 v3, v0, v3
	v_cndmask_b32_e64 v0, v3, v0, s[28:29]
	ds_bpermute_b32 v3, v120, v0
	v_readlane_b32 s28, v255, 28
	v_readlane_b32 s29, v255, 29
	s_waitcnt lgkmcnt(0)
	v_add_f32_e32 v3, v0, v3
	v_cndmask_b32_e64 v0, v3, v0, s[28:29]
	ds_bpermute_b32 v3, v121, v0
	v_readlane_b32 s28, v255, 30
	v_readlane_b32 s29, v255, 31
	s_waitcnt lgkmcnt(0)
	v_add_f32_e32 v3, v0, v3
	v_cndmask_b32_e64 v0, v3, v0, s[28:29]
	ds_bpermute_b32 v3, v122, v0
	v_readlane_b32 s28, v255, 32
	v_readlane_b32 s29, v255, 33
	s_waitcnt lgkmcnt(0)
	v_add_f32_e32 v3, v0, v3
	v_cndmask_b32_e64 v0, v3, v0, s[28:29]
	s_waitcnt vmcnt(0)
	ds_write2st64_b32 v109, v0, v2 offset1:2
